# stack: write-through stores + barrier without wbl2, L1 invalidate on wave 1, re-stagger barrier moved behind next_unit/zeroing, relaxed first two vmcnt waits after an epilogue
# baseline (speedup 1.0000x reference)
; __device__ __forceinline__ void xcd_barrier(const XcdBarrier& b) {
;     ...
;         asm volatile("s_waitcnt vmcnt(0)" ::: "memory");
;         b.st[2] = target;
;     }
;     __syncthreads();
.LBB0_9:
	s_or_b64 exec, exec, s[2:3]
	s_waitcnt vmcnt(0) lgkmcnt(0)
	s_barrier

; #define PG8_STAGE(bufoff, gbase, voff) do { _Pragma("unroll") for (int _i = 0; _i < 2; ++_i) { unsigned _vo = (voff)[_i]; asm volatile("" : "+v"(_vo));   \
;         __builtin_amdgcn_global_load_lds((const unsigned*)((const char*)(gbase) + _vo), (LAS unsigned*)(lds + (bufoff) + ldsw + _i * 8192), 16, 0, 0); } } while (0)
; #define PG8_WAIT_V(n) asm volatile("s_waitcnt vmcnt(" #n ")" ::: "memory")
; #define PG8_BAR __builtin_amdgcn_s_barrier()
; __device__ __forceinline__ void gemm_phase(LAS unsigned char* lds, const Call& C, const int tid, const Args& args) {
;     ...
;     const char* cA = PG8_APTR(cur); const char* cB = PG8_BPTR(cur);
;     PG8_STAGE(PG8_SB(0, 0), cB, voffB); PG8_STAGE(PG8_SB(0, 1), cB + hstepB, voffB); PG8_STAGE(PG8_SA(0, 0), cA, voffA); PG8_STAGE(PG8_SA(0, 1), cA + hstepA, voffA);
;     if (wr == 1) PG8_BAR;
;     PG8_WAIT_V(2); PG8_BAR;
;     PG8_STAGE(PG8_SB(1, 0), cB + kstep, voffB); PG8_STAGE(PG8_SA(1, 0), cA + kstep, voffA); PG8_STAGE(PG8_SB(1, 1), cB + hstepB + kstep, voffB);
;     PG8_WAIT_V(6); PG8_BAR;
;     for (;;) {
;         next_unit(C, ui + 1, nxt.pm, nxt.pn, nxt.kp0, nxt.np, nxt.slice);
;         const bool has_next = nxt.pm >= 0;
;         const char* nA = has_next ? PG8_APTR(nxt) : cA; const char* nB = has_next ? PG8_BPTR(nxt) : cB;
;         const int nt = 2 * cur.np;
.LBB0_264:
	v_mov_b32_e32 v80, v242
	s_waitcnt vmcnt(2)
	s_barrier
	s_add_i32 m0, s20, 0x18000
	v_lshl_add_u64 v[0:1], s[8:9], 0, v[80:81]
	v_lshl_add_u64 v[0:1], v[0:1], 0, s[18:19]
	v_mov_b32_e32 v80, v244
	global_load_lds_dwordx4 v[0:1], off
	s_add_i32 m0, s20, 0x1a000
	v_lshl_add_u64 v[0:1], s[8:9], 0, v[80:81]
	v_lshl_add_u64 v[0:1], v[0:1], 0, s[18:19]
	v_mov_b32_e32 v80, v205
	global_load_lds_dwordx4 v[0:1], off
	s_add_i32 s14, s20, 0x8000
	v_lshl_add_u64 v[0:1], s[0:1], 0, v[80:81]
	v_lshl_add_u64 v[0:1], v[0:1], 0, s[18:19]
	s_mov_b32 m0, s14
	v_mov_b32_e32 v80, v243
	global_load_lds_dwordx4 v[0:1], off
	s_add_i32 s52, s20, 0xa000
	v_lshl_add_u64 v[0:1], s[0:1], 0, v[80:81]
	v_lshl_add_u64 v[0:1], v[0:1], 0, s[18:19]
	s_mov_b32 m0, s52
	v_mov_b32_e32 v80, v242
	s_and_b32 s24, s12, 3
	global_load_lds_dwordx4 v[0:1], off
	s_lshl_b32 s27, s13, 6
	v_lshl_add_u64 v[0:1], s[34:35], 0, v[80:81]
	s_lshl_b32 s17, s13, 13
	s_lshl_b32 s13, s24, 5
	s_add_i32 m0, s20, 0x1c000
	v_lshl_add_u64 v[0:1], v[0:1], 0, s[18:19]
	v_writelane_b32 v254, s13, 59
	s_lshl_b32 s13, s24, 12
	global_load_lds_dwordx4 v[0:1], off
	s_add_i32 m0, s20, 0x1e000
	s_cmpk_lt_u32 s5, 0x100
	v_mov_b32_e32 v80, v244
	s_cselect_b64 s[80:81], -1, 0
	s_bitcmp0_b32 s5, 6
	s_mov_b32 s97, s29
	v_lshl_add_u64 v[0:1], s[34:35], 0, v[80:81]
	s_cselect_b64 s[34:35], -1, 0
	s_lshl_b32 s25, s24, 4
	v_writelane_b32 v254, s34, 60
	s_add_i32 s25, s25, 0
	s_add_i32 s25, s25, 0x20400
	v_writelane_b32 v254, s35, 61
	s_lshl_b32 s12, s12, 5
	v_writelane_b32 v254, s25, 62
	s_cmp_lt_u32 s5, 64
	v_writelane_b32 v254, s12, 63
	s_cselect_b64 s[34:35], -1, 0
	v_writelane_b32 v255, s34, 0
	s_ashr_i32 s53, s11, 31
	s_ashr_i32 s51, s21, 31
	v_readlane_b32 s47, v254, 38
	s_lshl_b32 s12, s24, 6
	v_readlane_b32 s24, v254, 23
	v_writelane_b32 v255, s35, 1
	s_mul_i32 s5, s47, s42
	v_readlane_b32 s25, v254, 24
	s_add_u32 s12, s24, s12
	v_readlane_b32 s43, v254, 16
	v_writelane_b32 v255, s12, 2
	s_addc_u32 s12, s25, 0
	s_mul_i32 s5, s5, s43
	v_writelane_b32 v255, s12, 3
	s_add_i32 s54, s5, s26
	s_lshr_b32 s5, s26, 3
	s_and_b32 s88, s26, 7
	v_writelane_b32 v255, s5, 4
	s_add_i32 s5, s5, 1
	s_lshl_b32 s45, s43, 2
	s_add_u32 s24, s48, 0x1000
	v_writelane_b32 v255, s5, 5
	s_addc_u32 s25, s49, 0
	v_writelane_b32 v255, s24, 6
	v_readlane_b32 s5, v254, 52
	s_add_i32 s5, s27, s5
	v_writelane_b32 v255, s25, 7
	v_writelane_b32 v255, s27, 8
	v_writelane_b32 v255, s5, 9
	s_ashr_i32 s5, s44, 1
	v_lshl_add_u64 v[0:1], v[0:1], 0, s[18:19]
	s_and_b32 s12, s44, 1
	s_bfe_i32 s28, s44, 0x10000
	s_lshl_b32 s24, s5, 3
	global_load_lds_dwordx4 v[0:1], off
	s_bitcmp1_b32 s44, 0
	v_writelane_b32 v255, s24, 10
	s_cselect_b64 s[24:25], -1, 0
	s_cmp_lg_u32 s5, 3
	s_cselect_b64 s[34:35], -1, 0
	s_cmp_eq_u32 s12, 0
	s_cselect_b64 s[36:37], -1, 0
	s_and_b64 s[38:39], s[36:37], exec
	s_movk_i32 s12, 0x1400
	s_movk_i32 s27, 0xc00
	s_cselect_b32 s12, 0x800, s12
	s_cselect_b32 s38, 0x400, s27
	s_cselect_b32 s39, s94, 0x400
	s_cselect_b32 s40, 0xc00, 0
	s_cselect_b32 s41, 0x800, 0
	s_or_b64 s[34:35], s[36:37], s[34:35]
	v_writelane_b32 v255, s34, 11
	s_lshl_b32 s27, s44, 12
	s_mov_b32 s55, s29
	v_writelane_b32 v255, s35, 12
	s_xor_b64 s[34:35], s[34:35], -1
	v_writelane_b32 v255, s34, 13
	s_waitcnt vmcnt(6)
	s_mov_b32 s92, 0
	s_movk_i32 s46, 0x1600
	v_writelane_b32 v255, s35, 14
	s_lshl_b32 s34, s5, 12
	s_or_b32 s34, s38, s34
	s_ashr_i32 s35, s34, 31
	s_lshl_b64 s[34:35], s[34:35], 2
	s_add_u32 s34, s68, s34
	v_writelane_b32 v255, s27, 15
	s_addc_u32 s35, s69, s35
	s_and_b32 s27, s28, 0x30000
	v_writelane_b32 v255, s34, 16
	s_cmp_lt_i32 s5, 3
	s_barrier
	v_writelane_b32 v255, s35, 17
	s_cselect_b64 s[34:35], -1, 0
	s_and_b64 s[24:25], s[24:25], s[34:35]
	v_cndmask_b32_e64 v2, 0, 1, s[24:25]
	v_writelane_b32 v255, s27, 18
	v_readfirstlane_b32 s24, v2
	s_add_i32 s5, s5, s24
	s_lshl_b32 s5, s5, 12
	v_cvt_f32_u32_e32 v2, s42
	s_or_b32 s24, s5, s41
	s_ashr_i32 s25, s24, 31
	s_lshl_b64 s[24:25], s[24:25], 2
	s_add_u32 s24, s68, s24
	v_rcp_iflag_f32_e32 v3, v2
	s_addc_u32 s25, s69, s25
	v_writelane_b32 v255, s24, 19
	v_readlane_b32 s27, v254, 41
	v_mul_f32_e32 v4, 0x4f7ffffe, v3
	v_writelane_b32 v255, s25, 20
	s_add_u32 s24, s48, 0x2c00
	s_addc_u32 s25, s49, 0
	v_writelane_b32 v255, s24, 21
	v_cvt_u32_f32_e32 v4, v4
	s_nop 0
	v_writelane_b32 v255, s25, 22
	s_add_u32 s24, s48, 0x5800
	s_addc_u32 s25, s49, 0
	v_writelane_b32 v255, s24, 23
	s_sub_i32 s5, 0, s42
	s_lshl_b32 s96, s43, 8
	v_writelane_b32 v255, s25, 24
	v_readfirstlane_b32 s24, v4
	v_cvt_f32_u32_e32 v4, s27
	s_mul_i32 s5, s5, s24
	s_mul_hi_u32 s5, s24, s5
	s_add_i32 s5, s24, s5
	v_mul_f32_e32 v3, v4, v3
	v_trunc_f32_e32 v3, v3
	v_fma_f32 v4, -v3, v2, v4
	v_cvt_u32_f32_e32 v3, v3
	v_writelane_b32 v255, s5, 25
	s_lshl_b64 s[82:83], s[96:97], 8
	v_cmp_ge_f32_e64 s[24:25], |v4|, v2
	v_and_b32_e32 v2, 48, v204
	v_lshlrev_b32_e32 v4, 6, v204
	s_movk_i32 s5, 0x3c0
	s_cmp_lg_u64 s[24:25], 0
	v_and_or_b32 v2, v4, s5, v2
	v_readfirstlane_b32 s5, v3
	s_addc_u32 s5, s5, 0
	s_abs_i32 s97, s43
	v_cvt_f32_u32_e32 v3, s97
	v_lshlrev_b32_e32 v4, 2, v204
	v_and_b32_e32 v4, 32, v4
	s_abs_i32 s93, s45
	v_bitop3_b32 v5, v2, s17, v4 bitop3:0xde
	v_rcp_iflag_f32_e32 v3, v3
	v_bitop3_b32 v245, s13, v2, v4 bitop3:0xf6
	v_cvt_f32_u32_e32 v2, s93
	s_sub_i32 s13, 0, s97
	v_mul_f32_e32 v3, 0x4f7ffffe, v3
	v_cvt_u32_f32_e32 v3, v3
	v_rcp_iflag_f32_e32 v2, v2
	s_and_b32 s5, s5, 31
	v_add_u32_e32 v246, 0, v5
	v_readfirstlane_b32 s17, v3
	v_mul_f32_e32 v2, 0x4f7ffffe, v2
	v_cvt_u32_f32_e32 v2, v2
	s_mul_i32 s13, s13, s17
	s_mul_hi_u32 s13, s17, s13
	s_add_i32 s13, s17, s13
	v_writelane_b32 v255, s13, 26
	s_sub_i32 s13, 0, s93
	v_readfirstlane_b32 s17, v2
	s_mul_i32 s13, s13, s17
	s_mul_hi_u32 s13, s17, s13
	v_writelane_b32 v255, s45, 27
	s_add_i32 s13, s17, s13
	v_writelane_b32 v255, s13, 28
	v_writelane_b32 v255, s5, 29
	s_mul_i32 s5, s5, s42
	s_sub_i32 s5, s27, s5
	v_writelane_b32 v255, s5, 30
	s_ashr_i32 s5, s43, 31
	v_writelane_b32 v255, s5, 31
	s_bfe_i32 s5, s43, 0x1001d
	v_writelane_b32 v255, s5, 32
	s_add_u32 s89, s22, 0x80
	v_writelane_b32 v255, s54, 33
	s_addc_u32 s94, 0, 0
	s_lshl_b32 s5, s12, 2
	v_writelane_b32 v255, s55, 34
	v_writelane_b32 v255, s5, 35
	s_lshl_b32 s12, s40, 2
	v_writelane_b32 v255, s12, 36
	s_lshl_b32 s28, s39, 2
	s_mov_b32 s27, s29
	v_writelane_b32 v255, s13, 37
	v_readlane_b32 s55, v254, 15
	s_mov_b32 s101, 0
	s_mov_b32 s100, 0
	s_branch .LBB0_267

; #define PG8_BAR __builtin_amdgcn_s_barrier()
; __device__ __forceinline__ void gemm_phase(LAS unsigned char* lds, const Call& C, const int tid, const Args& args) {
;     ...
;         if (!has_next) break;
; #pragma unroll
;         for (int a = 0; a < 2; ++a)
; #pragma unroll
;             for (int b = 0; b < 2; ++b)
; #pragma unroll
;                 for (int m = 0; m < 4; ++m)
; #pragma unroll
;                     for (int n = 0; n < 2; ++n) acc[a][b][m][n] = (f32x4){0.f, 0.f, 0.f, 0.f};
;         cur.pm = nxt.pm; cur.pn = nxt.pn; cur.kp0 = nxt.kp0; cur.np = nxt.np; cur.slice = nxt.slice; cA = nA; cB = nB; ++ui;
;         if (wr == 1) PG8_BAR;
.LBB0_266:
	s_mov_b32 s100, 1
	s_andn2_b64 vcc, exec, s[0:1]
	s_mov_b32 s50, s91
	s_mov_b32 s16, s54
	s_mov_b32 s78, s95
	s_mov_b32 s90, s5
	s_mov_b64 s[8:9], s[48:49]
	s_mov_b64 s[0:1], s[86:87]
	s_cbranch_vccz .LBB0_501

; #define PG8_STAGE(bufoff, gbase, voff) do { _Pragma("unroll") for (int _i = 0; _i < 2; ++_i) { unsigned _vo = (voff)[_i]; asm volatile("" : "+v"(_vo));   \
;         __builtin_amdgcn_global_load_lds((const unsigned*)((const char*)(gbase) + _vo), (LAS unsigned*)(lds + (bufoff) + ldsw + _i * 8192), 16, 0, 0); } } while (0)
; #define PG8_LDA(dst, b, h) do { _Pragma("unroll") for (int m = 0; m < 4; ++m) _Pragma("unroll") for (int k = 0; k < 2; ++k) dst[m][k] = *(const LAS bf16x8*)(lds + PG8_SA(b, h) + aoff + m * 2048 + k * 1024); } while (0)
; #define PG8_LDB(dst, b, h) do { _Pragma("unroll") for (int n = 0; n < 2; ++n) _Pragma("unroll") for (int k = 0; k < 2; ++k) dst[n][k] = *(const LAS bf16x8*)(lds + PG8_SB(b, h) + boff + n * 2048 + k * 1024); } while (0)
; #define PG8_MMA(ai, bj, At, Bt) do { __builtin_amdgcn_s_setprio(1); _Pragma("unroll") for (int m = 0; m < 4; ++m) _Pragma("unroll") for (int n = 0; n < 2; ++n) _Pragma("unroll") for (int k = 0; k < 2; ++k) \
;         acc[ai][bj][m][n] = __builtin_amdgcn_mfma_f32_16x16x32_bf16(Bt[n][k], At[m][k], acc[ai][bj][m][n], 0, 0, 0); __builtin_amdgcn_s_setprio(0); } while (0)
; #define PG8_WAIT_V(n) asm volatile("s_waitcnt vmcnt(" #n ")" ::: "memory")
; __device__ __forceinline__ void gemm_phase(LAS unsigned char* lds, const Call& C, const int tid, const Args& args) {
;     ...
;         for (int t = 0; t < nt; t += 2) {
;             const bool last = (t == nt - 2);
;             const char* a1 = cA + (size_t)(t + 1) * kstep;
;             const char* a2 = last ? nA : cA + (size_t)(t + 2) * kstep; const char* b2 = last ? nB : cB + (size_t)(t + 2) * kstep;
;             const char* a3 = a2 + kstep; const char* b3 = b2 + kstep;
;             PG8_LDB(B0, 0, 0); PG8_LDB(B1, 0, 1); PG8_SCHED; PG8_LDA(At, 0, 0); PG8_STAGE(PG8_SA(1, 1), a1 + hstepA, voffA);
;             PG8_WAIT_V(8); PG8_WAIT_L(0); PG8_BAR; PG8_MMA(0, 0, At, B0); PG8_MMA(0, 1, At, B1); PG8_BAR; PG8_SCHED;
;     ...
; #pragma unroll
;         for (int a = 0; a < 2; ++a)
; #pragma unroll
;             for (int b = 0; b < 2; ++b)
; #pragma unroll
;                 for (int m = 0; m < 4; ++m)
; #pragma unroll
;                     for (int n = 0; n < 2; ++n) acc[a][b][m][n] = (f32x4){0.f, 0.f, 0.f, 0.f};
;         cur.pm = nxt.pm; cur.pn = nxt.pn; cur.kp0 = nxt.kp0; cur.np = nxt.np; cur.slice = nxt.slice; cA = nA; cB = nB; ++ui;
;         if (wr == 1) PG8_BAR;
.LBB0_280:
	s_cmp_eq_u32 s16, 0
	s_cbranch_scc1 .LBB0_313
	s_lshl_b32 s12, s16, 1
	s_add_i32 s13, s12, -2
	s_add_u32 s16, s8, 0x100
	v_mov_b32_e32 v0, 0
	s_addc_u32 s17, s9, 0
	s_mov_b32 s24, 0
	v_mov_b32_e32 v1, v0
	v_mov_b32_e32 v2, v0
	v_mov_b32_e32 v3, v0
	v_mov_b32_e32 v4, v0
	v_mov_b32_e32 v5, v0
	v_mov_b32_e32 v6, v0
	v_mov_b32_e32 v7, v0
	v_mov_b32_e32 v8, v0
	s_waitcnt lgkmcnt(0)
	v_mov_b32_e32 v9, v0
	v_mov_b32_e32 v10, v0
	v_mov_b32_e32 v11, v0
	v_mov_b32_e32 v12, v0
	v_mov_b32_e32 v13, v0
	v_mov_b32_e32 v14, v0
	v_mov_b32_e32 v15, v0
	v_mov_b32_e32 v24, v0
	v_mov_b32_e32 v25, v0
	v_mov_b32_e32 v26, v0
	v_mov_b32_e32 v27, v0
	v_mov_b32_e32 v28, v0
	v_mov_b32_e32 v29, v0
	v_mov_b32_e32 v30, v0
	v_mov_b32_e32 v31, v0
	v_mov_b32_e32 v40, v0
	v_mov_b32_e32 v41, v0
	v_mov_b32_e32 v42, v0
	v_mov_b32_e32 v43, v0
	v_mov_b32_e32 v44, v0
	v_mov_b32_e32 v45, v0
	v_mov_b32_e32 v46, v0
	v_mov_b32_e32 v47, v0
	v_mov_b32_e32 v16, v0
	v_mov_b32_e32 v17, v0
	v_mov_b32_e32 v18, v0
	v_mov_b32_e32 v19, v0
	v_mov_b32_e32 v20, v0
	v_mov_b32_e32 v21, v0
	v_mov_b32_e32 v22, v0
	v_mov_b32_e32 v23, v0
	v_mov_b32_e32 v32, v0
	v_mov_b32_e32 v33, v0
	v_mov_b32_e32 v34, v0
	v_mov_b32_e32 v35, v0
	v_mov_b32_e32 v36, v0
	v_mov_b32_e32 v37, v0
	v_mov_b32_e32 v38, v0
	v_mov_b32_e32 v39, v0
	v_mov_b32_e32 v48, v0
	v_mov_b32_e32 v49, v0
	v_mov_b32_e32 v50, v0
	v_mov_b32_e32 v51, v0
	v_mov_b32_e32 v52, v0
	v_mov_b32_e32 v53, v0
	v_mov_b32_e32 v54, v0
	v_mov_b32_e32 v55, v0
	v_mov_b32_e32 v56, v0
	v_mov_b32_e32 v57, v0
	v_mov_b32_e32 v58, v0
	v_mov_b32_e32 v59, v0
	v_mov_b32_e32 v64, v0
	v_mov_b32_e32 v65, v0
	v_mov_b32_e32 v66, v0
	v_mov_b32_e32 v67, v0
	v_mov_b32_e32 v60, v0
	v_mov_b32_e32 v61, v0
	v_mov_b32_e32 v62, v0
	v_mov_b32_e32 v63, v0
	v_mov_b32_e32 v68, v0
	v_mov_b32_e32 v69, v0
	v_mov_b32_e32 v70, v0
	v_mov_b32_e32 v71, v0
	v_mov_b32_e32 v72, v0
	v_mov_b32_e32 v73, v0
	v_mov_b32_e32 v74, v0
	v_mov_b32_e32 v75, v0
	v_mov_b32_e32 v76, v0
	v_mov_b32_e32 v77, v0
	v_mov_b32_e32 v78, v0
	v_mov_b32_e32 v79, v0
	v_mov_b32_e32 v96, v0
	v_mov_b32_e32 v97, v0
	v_mov_b32_e32 v98, v0
	v_mov_b32_e32 v99, v0
	v_mov_b32_e32 v100, v0
	v_mov_b32_e32 v101, v0
	v_mov_b32_e32 v102, v0
	v_mov_b32_e32 v103, v0
	v_mov_b32_e32 v112, v0
	v_mov_b32_e32 v113, v0
	v_mov_b32_e32 v114, v0
	v_mov_b32_e32 v115, v0
	v_mov_b32_e32 v116, v0
	v_mov_b32_e32 v117, v0
	v_mov_b32_e32 v118, v0
	v_mov_b32_e32 v119, v0
	v_mov_b32_e32 v88, v0
	v_mov_b32_e32 v89, v0
	v_mov_b32_e32 v90, v0
	v_mov_b32_e32 v91, v0
	v_mov_b32_e32 v92, v0
	v_mov_b32_e32 v93, v0
	v_mov_b32_e32 v94, v0
	v_mov_b32_e32 v95, v0
	v_mov_b32_e32 v104, v0
	v_mov_b32_e32 v105, v0
	v_mov_b32_e32 v106, v0
	v_mov_b32_e32 v107, v0
	v_mov_b32_e32 v108, v0
	v_mov_b32_e32 v109, v0
	v_mov_b32_e32 v110, v0
	v_mov_b32_e32 v111, v0
	v_mov_b32_e32 v120, v0
	v_mov_b32_e32 v121, v0
	v_mov_b32_e32 v122, v0
	v_mov_b32_e32 v123, v0
	v_mov_b32_e32 v124, v0
	v_mov_b32_e32 v125, v0
	v_mov_b32_e32 v126, v0
	v_mov_b32_e32 v127, v0
	v_mov_b32_e32 v128, v0
	v_mov_b32_e32 v129, v0
	v_mov_b32_e32 v130, v0
	v_mov_b32_e32 v131, v0
	v_mov_b32_e32 v132, v0
	v_mov_b32_e32 v133, v0
	v_mov_b32_e32 v134, v0
	v_mov_b32_e32 v135, v0
	s_cmp_eq_u32 s101, 0
	s_cbranch_scc1 .Lbf1_nb
	s_barrier
.Lbf1_nb:
.LBB0_282:
	s_add_i32 s25, s24, 2
	s_add_u32 s8, s0, 0x100
	s_addc_u32 s9, s1, 0
	s_add_i32 s34, 0, 0x10000
	s_cmp_eq_u32 s13, s24
	s_cselect_b32 s39, s87, s9
	s_cselect_b32 s38, s86, s8
	v_add_u32_e32 v80, s34, v245
	s_cselect_b32 s41, s49, s17
	s_cselect_b32 s40, s48, s16
	s_add_i32 s24, 0, 0x14000
	ds_read_b128 v[136:139], v80
	ds_read_b128 v[140:143], v80 offset:1024
	ds_read_b128 v[144:147], v80 offset:2048
	ds_read_b128 v[148:151], v80 offset:3072
	v_add_u32_e32 v80, s24, v245
	ds_read_b128 v[152:155], v80
	ds_read_b128 v[156:159], v80 offset:1024
	ds_read_b128 v[160:163], v80 offset:2048
	ds_read_b128 v[164:167], v80 offset:3072
	v_mov_b32_e32 v80, v205
	s_add_u32 s0, s0, s89
	ds_read_b128 v[168:171], v246
	ds_read_b128 v[172:175], v246 offset:1024
	ds_read_b128 v[176:179], v246 offset:2048
	ds_read_b128 v[180:183], v246 offset:3072
	ds_read_b128 v[184:187], v246 offset:4096
	ds_read_b128 v[188:191], v246 offset:5120
	ds_read_b128 v[192:195], v246 offset:6144
	ds_read_b128 v[196:199], v246 offset:7168
	s_addc_u32 s1, s1, s94
	s_add_i32 m0, s20, 0xc000
	s_nop 0
	global_load_lds_dwordx4 v80, s[0:1]
	v_mov_b32_e32 v80, v243
	s_add_i32 m0, s20, 0xe000
	s_nop 0
	global_load_lds_dwordx4 v80, s[0:1]
	s_cmp_eq_u32 s100, 0
	s_cbranch_scc1 .Lt3_p1_n
	s_waitcnt vmcnt(24)
	s_branch .Lt3_p1_j
; #define PG8_STAGE(bufoff, gbase, voff) do { _Pragma("unroll") for (int _i = 0; _i < 2; ++_i) { unsigned _vo = (voff)[_i]; asm volatile("" : "+v"(_vo));   \
;         __builtin_amdgcn_global_load_lds((const unsigned*)((const char*)(gbase) + _vo), (LAS unsigned*)(lds + (bufoff) + ldsw + _i * 8192), 16, 0, 0); } } while (0)
; #define PG8_LDA(dst, b, h) do { _Pragma("unroll") for (int m = 0; m < 4; ++m) _Pragma("unroll") for (int k = 0; k < 2; ++k) dst[m][k] = *(const LAS bf16x8*)(lds + PG8_SA(b, h) + aoff + m * 2048 + k * 1024); } while (0)
; #define PG8_MMA(ai, bj, At, Bt) do { __builtin_amdgcn_s_setprio(1); _Pragma("unroll") for (int m = 0; m < 4; ++m) _Pragma("unroll") for (int n = 0; n < 2; ++n) _Pragma("unroll") for (int k = 0; k < 2; ++k) \
;         acc[ai][bj][m][n] = __builtin_amdgcn_mfma_f32_16x16x32_bf16(Bt[n][k], At[m][k], acc[ai][bj][m][n], 0, 0, 0); __builtin_amdgcn_s_setprio(0); } while (0)
; #define PG8_WAIT_V(n) asm volatile("s_waitcnt vmcnt(" #n ")" ::: "memory")
; #define PG8_WAIT_L(n) asm volatile("s_waitcnt lgkmcnt(" #n ")" ::: "memory")
; #define PG8_BAR __builtin_amdgcn_s_barrier()
; #define PG8_SCHED __builtin_amdgcn_sched_barrier(0)
; __device__ __forceinline__ void gemm_phase(LAS unsigned char* lds, const Call& C, const int tid, const Args& args) {
;     ...
;             PG8_WAIT_V(8); PG8_WAIT_L(0); PG8_BAR; PG8_MMA(0, 0, At, B0); PG8_MMA(0, 1, At, B1); PG8_BAR; PG8_SCHED;
;             PG8_LDA(At, 0, 1); PG8_STAGE(PG8_SB(0, 0), b2, voffB); PG8_STAGE(PG8_SB(0, 1), b2 + hstepB, voffB); PG8_STAGE(PG8_SA(0, 0), a2, voffA);
;             PG8_WAIT_V(8); PG8_WAIT_L(0); PG8_BAR; PG8_MMA(1, 0, At, B0); PG8_MMA(1, 1, At, B1); PG8_BAR; PG8_SCHED;
.Lt3_p1_n:
	s_waitcnt vmcnt(8)
.Lt3_p1_j:
	s_waitcnt lgkmcnt(0)
	s_barrier
	s_setprio 1
	s_waitcnt lgkmcnt(0)
	v_mfma_f32_16x16x32_bf16 v[132:135], v[136:139], v[168:171], v[132:135]
	v_mfma_f32_16x16x32_bf16 v[128:131], v[144:147], v[168:171], v[128:131]
	v_mfma_f32_16x16x32_bf16 v[124:127], v[136:139], v[176:179], v[124:127]
	v_mfma_f32_16x16x32_bf16 v[120:123], v[144:147], v[176:179], v[120:123]
	v_mfma_f32_16x16x32_bf16 v[108:111], v[136:139], v[184:187], v[108:111]
	v_mfma_f32_16x16x32_bf16 v[104:107], v[144:147], v[184:187], v[104:107]
	v_mfma_f32_16x16x32_bf16 v[92:95], v[136:139], v[192:195], v[92:95]
	v_mfma_f32_16x16x32_bf16 v[86:89], v[144:147], v[192:195], v[88:91]
	v_mfma_f32_16x16x32_bf16 v[132:135], v[140:143], v[172:175], v[132:135]
	v_mfma_f32_16x16x32_bf16 v[128:131], v[148:151], v[172:175], v[128:131]
	v_mfma_f32_16x16x32_bf16 v[124:127], v[140:143], v[180:183], v[124:127]
	v_mfma_f32_16x16x32_bf16 v[120:123], v[148:151], v[180:183], v[120:123]
	v_mfma_f32_16x16x32_bf16 v[108:111], v[140:143], v[188:191], v[108:111]
	v_mfma_f32_16x16x32_bf16 v[104:107], v[148:151], v[188:191], v[104:107]
	v_mfma_f32_16x16x32_bf16 v[92:95], v[140:143], v[196:199], v[92:95]
	v_mfma_f32_16x16x32_bf16 v[86:89], v[148:151], v[196:199], v[86:89]
	s_setprio 0
	s_setprio 1
	v_mfma_f32_16x16x32_bf16 v[116:119], v[152:155], v[168:171], v[116:119]
	v_mfma_f32_16x16x32_bf16 v[112:115], v[160:163], v[168:171], v[112:115]
	v_mfma_f32_16x16x32_bf16 v[100:103], v[152:155], v[176:179], v[100:103]
	v_mfma_f32_16x16x32_bf16 v[96:99], v[160:163], v[176:179], v[96:99]
	v_mfma_f32_16x16x32_bf16 v[76:79], v[152:155], v[184:187], v[76:79]
	v_mfma_f32_16x16x32_bf16 v[72:75], v[160:163], v[184:187], v[72:75]
	v_mfma_f32_16x16x32_bf16 v[68:71], v[152:155], v[192:195], v[68:71]
	v_mfma_f32_16x16x32_bf16 v[60:63], v[160:163], v[192:195], v[60:63]
	v_mfma_f32_16x16x32_bf16 v[116:119], v[156:159], v[172:175], v[116:119]
	v_mfma_f32_16x16x32_bf16 v[112:115], v[164:167], v[172:175], v[112:115]
	v_mfma_f32_16x16x32_bf16 v[100:103], v[156:159], v[180:183], v[100:103]
	v_mfma_f32_16x16x32_bf16 v[96:99], v[164:167], v[180:183], v[96:99]
	v_mfma_f32_16x16x32_bf16 v[76:79], v[156:159], v[188:191], v[76:79]
	v_mfma_f32_16x16x32_bf16 v[72:75], v[164:167], v[188:191], v[72:75]
	v_mfma_f32_16x16x32_bf16 v[68:71], v[156:159], v[196:199], v[68:71]
	v_mfma_f32_16x16x32_bf16 v[60:63], v[164:167], v[196:199], v[60:63]
	s_setprio 0
	s_barrier
	v_mov_b32_e32 v80, v242
	s_add_i32 s0, s34, s23
	ds_read_b128 v[168:171], v246 offset:16384
	ds_read_b128 v[172:175], v246 offset:17408
	ds_read_b128 v[176:179], v246 offset:18432
	ds_read_b128 v[180:183], v246 offset:19456
	ds_read_b128 v[184:187], v246 offset:20480
	ds_read_b128 v[188:191], v246 offset:21504
	ds_read_b128 v[192:195], v246 offset:22528
	ds_read_b128 v[196:199], v246 offset:23552
	s_mov_b32 m0, s0
	s_nop 0
	global_load_lds_dwordx4 v80, s[40:41]
	v_mov_b32_e32 v80, v244
	s_add_i32 m0, s0, 0x2000
	s_add_u32 s0, s40, s74
	global_load_lds_dwordx4 v80, s[40:41]
	s_addc_u32 s1, s41, s75
	v_mov_b32_e32 v80, v242
	s_add_i32 s24, s24, s23
	s_mov_b32 m0, s24
	s_nop 0
	global_load_lds_dwordx4 v80, s[0:1]
	v_mov_b32_e32 v80, v244
	s_add_i32 m0, s24, 0x2000
	s_nop 0
	global_load_lds_dwordx4 v80, s[0:1]
	v_mov_b32_e32 v80, v205
	s_mov_b32 m0, s20
	s_nop 0
	global_load_lds_dwordx4 v80, s[38:39]
	v_mov_b32_e32 v80, v243
	s_mov_b32 m0, s72
	s_nop 0
	global_load_lds_dwordx4 v80, s[38:39]
	s_cmp_eq_u32 s100, 0
	s_cbranch_scc1 .Lt3_p2_n
	s_waitcnt vmcnt(24)
	s_mov_b32 s100, 0
	s_branch .Lt3_p2_j

; #define PG8_STAGE(bufoff, gbase, voff) do { _Pragma("unroll") for (int _i = 0; _i < 2; ++_i) { unsigned _vo = (voff)[_i]; asm volatile("" : "+v"(_vo));   \
;         __builtin_amdgcn_global_load_lds((const unsigned*)((const char*)(gbase) + _vo), (LAS unsigned*)(lds + (bufoff) + ldsw + _i * 8192), 16, 0, 0); } } while (0)
; #define PG8_LDA(dst, b, h) do { _Pragma("unroll") for (int m = 0; m < 4; ++m) _Pragma("unroll") for (int k = 0; k < 2; ++k) dst[m][k] = *(const LAS bf16x8*)(lds + PG8_SA(b, h) + aoff + m * 2048 + k * 1024); } while (0)
; #define PG8_LDB(dst, b, h) do { _Pragma("unroll") for (int n = 0; n < 2; ++n) _Pragma("unroll") for (int k = 0; k < 2; ++k) dst[n][k] = *(const LAS bf16x8*)(lds + PG8_SB(b, h) + boff + n * 2048 + k * 1024); } while (0)
; #define PG8_MMA(ai, bj, At, Bt) do { __builtin_amdgcn_s_setprio(1); _Pragma("unroll") for (int m = 0; m < 4; ++m) _Pragma("unroll") for (int n = 0; n < 2; ++n) _Pragma("unroll") for (int k = 0; k < 2; ++k) \
;         acc[ai][bj][m][n] = __builtin_amdgcn_mfma_f32_16x16x32_bf16(Bt[n][k], At[m][k], acc[ai][bj][m][n], 0, 0, 0); __builtin_amdgcn_s_setprio(0); } while (0)
; #define PG8_WAIT_V(n) asm volatile("s_waitcnt vmcnt(" #n ")" ::: "memory")
; #define PG8_WAIT_L(n) asm volatile("s_waitcnt lgkmcnt(" #n ")" ::: "memory")
; #define PG8_BAR __builtin_amdgcn_s_barrier()
; #define PG8_SCHED __builtin_amdgcn_sched_barrier(0)
; __device__ __forceinline__ void gemm_phase(LAS unsigned char* lds, const Call& C, const int tid, const Args& args) {
;     ...
;             PG8_WAIT_V(8); PG8_WAIT_L(0); PG8_BAR; PG8_MMA(1, 0, At, B0); PG8_MMA(1, 1, At, B1); PG8_BAR; PG8_SCHED;
;             PG8_LDB(B0, 1, 0); PG8_LDB(B1, 1, 1); PG8_SCHED; PG8_LDA(At, 1, 0); PG8_STAGE(PG8_SA(0, 1), a2 + hstepA, voffA);
;             PG8_WAIT_V(8); PG8_WAIT_L(0); PG8_BAR; PG8_MMA(0, 0, At, B0); PG8_MMA(0, 1, At, B1); PG8_BAR; PG8_SCHED;
.Lt3_p2_j:
	s_waitcnt lgkmcnt(0)
	s_barrier
	s_setprio 1
	s_waitcnt lgkmcnt(0)
	v_mfma_f32_16x16x32_bf16 v[64:67], v[136:139], v[168:171], v[64:67]
	v_mfma_f32_16x16x32_bf16 v[56:59], v[144:147], v[168:171], v[56:59]
	v_mfma_f32_16x16x32_bf16 v[52:55], v[136:139], v[176:179], v[52:55]
	v_mfma_f32_16x16x32_bf16 v[48:51], v[144:147], v[176:179], v[48:51]
	v_mfma_f32_16x16x32_bf16 v[36:39], v[136:139], v[184:187], v[36:39]
	v_mfma_f32_16x16x32_bf16 v[32:35], v[144:147], v[184:187], v[32:35]
	v_mfma_f32_16x16x32_bf16 v[20:23], v[136:139], v[192:195], v[20:23]
	v_mfma_f32_16x16x32_bf16 v[16:19], v[144:147], v[192:195], v[16:19]
	v_mfma_f32_16x16x32_bf16 v[64:67], v[140:143], v[172:175], v[64:67]
	v_mfma_f32_16x16x32_bf16 v[56:59], v[148:151], v[172:175], v[56:59]
	v_mfma_f32_16x16x32_bf16 v[52:55], v[140:143], v[180:183], v[52:55]
	v_mfma_f32_16x16x32_bf16 v[48:51], v[148:151], v[180:183], v[48:51]
	v_mfma_f32_16x16x32_bf16 v[36:39], v[140:143], v[188:191], v[36:39]
	v_mfma_f32_16x16x32_bf16 v[32:35], v[148:151], v[188:191], v[32:35]
	v_mfma_f32_16x16x32_bf16 v[20:23], v[140:143], v[196:199], v[20:23]
	v_mfma_f32_16x16x32_bf16 v[16:19], v[148:151], v[196:199], v[16:19]
	s_setprio 0
	s_setprio 1
	v_mfma_f32_16x16x32_bf16 v[44:47], v[152:155], v[168:171], v[44:47]
	v_mfma_f32_16x16x32_bf16 v[40:43], v[160:163], v[168:171], v[40:43]
	v_mfma_f32_16x16x32_bf16 v[28:31], v[152:155], v[176:179], v[28:31]
	v_mfma_f32_16x16x32_bf16 v[24:27], v[160:163], v[176:179], v[24:27]
	v_mfma_f32_16x16x32_bf16 v[12:15], v[152:155], v[184:187], v[12:15]
	v_mfma_f32_16x16x32_bf16 v[8:11], v[160:163], v[184:187], v[8:11]
	v_mfma_f32_16x16x32_bf16 v[4:7], v[152:155], v[192:195], v[4:7]
	v_mfma_f32_16x16x32_bf16 v[0:3], v[160:163], v[192:195], v[0:3]
	v_mfma_f32_16x16x32_bf16 v[44:47], v[156:159], v[172:175], v[44:47]
	v_mfma_f32_16x16x32_bf16 v[40:43], v[164:167], v[172:175], v[40:43]
	v_mfma_f32_16x16x32_bf16 v[28:31], v[156:159], v[180:183], v[28:31]
	v_mfma_f32_16x16x32_bf16 v[24:27], v[164:167], v[180:183], v[24:27]
	v_mfma_f32_16x16x32_bf16 v[12:15], v[156:159], v[188:191], v[12:15]
	v_mfma_f32_16x16x32_bf16 v[8:11], v[164:167], v[188:191], v[8:11]
	v_mfma_f32_16x16x32_bf16 v[4:7], v[156:159], v[196:199], v[4:7]
	v_mfma_f32_16x16x32_bf16 v[0:3], v[164:167], v[196:199], v[0:3]
	s_setprio 0
	s_barrier
	s_add_i32 s24, 0, 0x18000
	v_add_u32_e32 v80, s24, v245
	s_add_i32 s42, 0, 0x1c000
	ds_read_b128 v[136:139], v80
	ds_read_b128 v[140:143], v80 offset:1024
	ds_read_b128 v[144:147], v80 offset:2048
	ds_read_b128 v[148:151], v80 offset:3072
	v_add_u32_e32 v80, s42, v245
	ds_read_b128 v[152:155], v80
	ds_read_b128 v[156:159], v80 offset:1024
	ds_read_b128 v[160:163], v80 offset:2048
	ds_read_b128 v[164:167], v80 offset:3072
	s_add_u32 s34, s38, s22
	v_mov_b32_e32 v80, v205
	s_mov_b32 m0, s73
	ds_read_b128 v[168:171], v246 offset:32768
	ds_read_b128 v[172:175], v246 offset:33792
	ds_read_b128 v[176:179], v246 offset:34816
	ds_read_b128 v[180:183], v246 offset:35840
	ds_read_b128 v[184:187], v246 offset:36864
	ds_read_b128 v[188:191], v246 offset:37888
	ds_read_b128 v[192:195], v246 offset:38912
	ds_read_b128 v[196:199], v246 offset:39936
	s_addc_u32 s35, s39, 0
	s_nop 0
	global_load_lds_dwordx4 v80, s[34:35]
	v_mov_b32_e32 v80, v243
	s_mov_b32 m0, s4
	s_nop 0
	global_load_lds_dwordx4 v80, s[34:35]
	s_waitcnt vmcnt(8)
	s_waitcnt lgkmcnt(0)
	s_barrier
	s_setprio 1
	s_waitcnt lgkmcnt(0)
	v_mfma_f32_16x16x32_bf16 v[132:135], v[136:139], v[168:171], v[132:135]
	v_mfma_f32_16x16x32_bf16 v[128:131], v[144:147], v[168:171], v[128:131]
	v_mfma_f32_16x16x32_bf16 v[124:127], v[136:139], v[176:179], v[124:127]
	v_mfma_f32_16x16x32_bf16 v[120:123], v[144:147], v[176:179], v[120:123]
	v_mfma_f32_16x16x32_bf16 v[108:111], v[136:139], v[184:187], v[108:111]
	v_mfma_f32_16x16x32_bf16 v[104:107], v[144:147], v[184:187], v[104:107]
	v_mfma_f32_16x16x32_bf16 v[90:93], v[136:139], v[192:195], v[92:95]
	v_mfma_f32_16x16x32_bf16 v[86:89], v[144:147], v[192:195], v[86:89]
	v_mfma_f32_16x16x32_bf16 v[132:135], v[140:143], v[172:175], v[132:135]
	v_mfma_f32_16x16x32_bf16 v[128:131], v[148:151], v[172:175], v[128:131]
	v_mfma_f32_16x16x32_bf16 v[124:127], v[140:143], v[180:183], v[124:127]
	v_mfma_f32_16x16x32_bf16 v[120:123], v[148:151], v[180:183], v[120:123]
	v_mfma_f32_16x16x32_bf16 v[108:111], v[140:143], v[188:191], v[108:111]
	v_mfma_f32_16x16x32_bf16 v[104:107], v[148:151], v[188:191], v[104:107]
	v_mfma_f32_16x16x32_bf16 v[92:95], v[140:143], v[196:199], v[90:93]
	v_mfma_f32_16x16x32_bf16 v[88:91], v[148:151], v[196:199], v[86:89]
	s_setprio 0
	s_setprio 1
	v_mfma_f32_16x16x32_bf16 v[116:119], v[152:155], v[168:171], v[116:119]
	v_mfma_f32_16x16x32_bf16 v[112:115], v[160:163], v[168:171], v[112:115]
	v_mfma_f32_16x16x32_bf16 v[100:103], v[152:155], v[176:179], v[100:103]
	v_mfma_f32_16x16x32_bf16 v[96:99], v[160:163], v[176:179], v[96:99]
	v_mfma_f32_16x16x32_bf16 v[76:79], v[152:155], v[184:187], v[76:79]
	v_mfma_f32_16x16x32_bf16 v[72:75], v[160:163], v[184:187], v[72:75]
	v_mfma_f32_16x16x32_bf16 v[68:71], v[152:155], v[192:195], v[68:71]
	v_mfma_f32_16x16x32_bf16 v[60:63], v[160:163], v[192:195], v[60:63]
	v_mfma_f32_16x16x32_bf16 v[116:119], v[156:159], v[172:175], v[116:119]
	v_mfma_f32_16x16x32_bf16 v[112:115], v[164:167], v[172:175], v[112:115]
	v_mfma_f32_16x16x32_bf16 v[100:103], v[156:159], v[180:183], v[100:103]
	v_mfma_f32_16x16x32_bf16 v[96:99], v[164:167], v[180:183], v[96:99]
	v_mfma_f32_16x16x32_bf16 v[76:79], v[156:159], v[188:191], v[76:79]
	v_mfma_f32_16x16x32_bf16 v[72:75], v[164:167], v[188:191], v[72:75]
	v_mfma_f32_16x16x32_bf16 v[68:71], v[156:159], v[196:199], v[68:71]
	v_mfma_f32_16x16x32_bf16 v[60:63], v[164:167], v[196:199], v[60:63]
	s_setprio 0
	s_barrier
; #define PG8_STAGE(bufoff, gbase, voff) do { _Pragma("unroll") for (int _i = 0; _i < 2; ++_i) { unsigned _vo = (voff)[_i]; asm volatile("" : "+v"(_vo));   \
;         __builtin_amdgcn_global_load_lds((const unsigned*)((const char*)(gbase) + _vo), (LAS unsigned*)(lds + (bufoff) + ldsw + _i * 8192), 16, 0, 0); } } while (0)
; #define PG8_LDA(dst, b, h) do { _Pragma("unroll") for (int m = 0; m < 4; ++m) _Pragma("unroll") for (int k = 0; k < 2; ++k) dst[m][k] = *(const LAS bf16x8*)(lds + PG8_SA(b, h) + aoff + m * 2048 + k * 1024); } while (0)
; #define PG8_MMA(ai, bj, At, Bt) do { __builtin_amdgcn_s_setprio(1); _Pragma("unroll") for (int m = 0; m < 4; ++m) _Pragma("unroll") for (int n = 0; n < 2; ++n) _Pragma("unroll") for (int k = 0; k < 2; ++k) \
;         acc[ai][bj][m][n] = __builtin_amdgcn_mfma_f32_16x16x32_bf16(Bt[n][k], At[m][k], acc[ai][bj][m][n], 0, 0, 0); __builtin_amdgcn_s_setprio(0); } while (0)
; #define PG8_WAIT_V(n) asm volatile("s_waitcnt vmcnt(" #n ")" ::: "memory")
; #define PG8_WAIT_L(n) asm volatile("s_waitcnt lgkmcnt(" #n ")" ::: "memory")
; #define PG8_BAR __builtin_amdgcn_s_barrier()
; #define PG8_SCHED __builtin_amdgcn_sched_barrier(0)
; __device__ __forceinline__ void gemm_phase(LAS unsigned char* lds, const Call& C, const int tid, const Args& args) {
;     ...
;             PG8_LDA(At, 1, 1); PG8_STAGE(PG8_SB(1, 0), b3, voffB); PG8_STAGE(PG8_SB(1, 1), b3 + hstepB, voffB); PG8_STAGE(PG8_SA(1, 0), a3, voffA);
;             PG8_WAIT_V(8); PG8_WAIT_L(0); PG8_BAR; PG8_MMA(1, 0, At, B0); PG8_MMA(1, 1, At, B1); PG8_BAR; PG8_SCHED;
;         }
;         if (wr == 0) PG8_BAR;
	v_mov_b32_e32 v80, v242
	ds_read_b128 v[168:171], v246 offset:49152
	ds_read_b128 v[172:175], v246 offset:50176
	ds_read_b128 v[176:179], v246 offset:51200
	ds_read_b128 v[180:183], v246 offset:52224
	ds_read_b128 v[184:187], v246 offset:53248
	ds_read_b128 v[188:191], v246 offset:54272
	ds_read_b128 v[192:195], v246 offset:55296
	ds_read_b128 v[196:199], v246 offset:56320
	s_add_i32 s24, s24, s23
	v_lshl_add_u64 v[82:83], s[40:41], 0, v[80:81]
	v_lshl_add_u64 v[82:83], v[82:83], 0, s[18:19]
	s_mov_b32 m0, s24
	v_mov_b32_e32 v80, v244
	global_load_lds_dwordx4 v[82:83], off
	s_add_i32 m0, s24, 0x2000
	v_lshl_add_u64 v[82:83], s[40:41], 0, v[80:81]
	v_lshl_add_u64 v[82:83], v[82:83], 0, s[18:19]
	v_mov_b32_e32 v80, v242
	global_load_lds_dwordx4 v[82:83], off
	s_add_i32 s24, s42, s23
	v_lshl_add_u64 v[82:83], s[0:1], 0, v[80:81]
	v_lshl_add_u64 v[82:83], v[82:83], 0, s[18:19]
	s_mov_b32 m0, s24
	v_mov_b32_e32 v80, v244
	global_load_lds_dwordx4 v[82:83], off
	s_add_i32 m0, s24, 0x2000
	v_lshl_add_u64 v[82:83], s[0:1], 0, v[80:81]
	v_lshl_add_u64 v[82:83], v[82:83], 0, s[18:19]
	v_mov_b32_e32 v80, v205
	global_load_lds_dwordx4 v[82:83], off
	s_mov_b32 m0, s14
	v_lshl_add_u64 v[82:83], s[38:39], 0, v[80:81]
	v_lshl_add_u64 v[82:83], v[82:83], 0, s[18:19]
	v_mov_b32_e32 v80, v243
	global_load_lds_dwordx4 v[82:83], off
	s_mov_b32 m0, s52
	v_lshl_add_u64 v[82:83], s[38:39], 0, v[80:81]
	v_lshl_add_u64 v[82:83], v[82:83], 0, s[18:19]
	global_load_lds_dwordx4 v[82:83], off
	s_waitcnt vmcnt(8)
	s_waitcnt lgkmcnt(0)
	s_barrier
	s_setprio 1
	s_waitcnt lgkmcnt(0)
	v_mfma_f32_16x16x32_bf16 v[64:67], v[136:139], v[168:171], v[64:67]
	v_mfma_f32_16x16x32_bf16 v[56:59], v[144:147], v[168:171], v[56:59]
	v_mfma_f32_16x16x32_bf16 v[52:55], v[136:139], v[176:179], v[52:55]
	v_mfma_f32_16x16x32_bf16 v[48:51], v[144:147], v[176:179], v[48:51]
	v_mfma_f32_16x16x32_bf16 v[36:39], v[136:139], v[184:187], v[36:39]
	v_mfma_f32_16x16x32_bf16 v[32:35], v[144:147], v[184:187], v[32:35]
	v_mfma_f32_16x16x32_bf16 v[20:23], v[136:139], v[192:195], v[20:23]
	v_mfma_f32_16x16x32_bf16 v[16:19], v[144:147], v[192:195], v[16:19]
	v_mfma_f32_16x16x32_bf16 v[64:67], v[140:143], v[172:175], v[64:67]
	v_mfma_f32_16x16x32_bf16 v[56:59], v[148:151], v[172:175], v[56:59]
	v_mfma_f32_16x16x32_bf16 v[52:55], v[140:143], v[180:183], v[52:55]
	v_mfma_f32_16x16x32_bf16 v[48:51], v[148:151], v[180:183], v[48:51]
	v_mfma_f32_16x16x32_bf16 v[36:39], v[140:143], v[188:191], v[36:39]
	v_mfma_f32_16x16x32_bf16 v[32:35], v[148:151], v[188:191], v[32:35]
	v_mfma_f32_16x16x32_bf16 v[20:23], v[140:143], v[196:199], v[20:23]
	v_mfma_f32_16x16x32_bf16 v[16:19], v[148:151], v[196:199], v[16:19]
	s_setprio 0
	s_setprio 1
	v_mfma_f32_16x16x32_bf16 v[44:47], v[152:155], v[168:171], v[44:47]
	v_mfma_f32_16x16x32_bf16 v[40:43], v[160:163], v[168:171], v[40:43]
	v_mfma_f32_16x16x32_bf16 v[28:31], v[152:155], v[176:179], v[28:31]
	v_mfma_f32_16x16x32_bf16 v[24:27], v[160:163], v[176:179], v[24:27]
	v_mfma_f32_16x16x32_bf16 v[12:15], v[152:155], v[184:187], v[12:15]
	v_mfma_f32_16x16x32_bf16 v[8:11], v[160:163], v[184:187], v[8:11]
	v_mfma_f32_16x16x32_bf16 v[4:7], v[152:155], v[192:195], v[4:7]
	v_mfma_f32_16x16x32_bf16 v[0:3], v[160:163], v[192:195], v[0:3]
	v_mfma_f32_16x16x32_bf16 v[44:47], v[156:159], v[172:175], v[44:47]
	v_mfma_f32_16x16x32_bf16 v[40:43], v[164:167], v[172:175], v[40:43]
	v_mfma_f32_16x16x32_bf16 v[28:31], v[156:159], v[180:183], v[28:31]
	v_mfma_f32_16x16x32_bf16 v[24:27], v[164:167], v[180:183], v[24:27]
	v_mfma_f32_16x16x32_bf16 v[12:15], v[156:159], v[188:191], v[12:15]
	v_mfma_f32_16x16x32_bf16 v[8:11], v[164:167], v[188:191], v[8:11]
	v_mfma_f32_16x16x32_bf16 v[4:7], v[156:159], v[196:199], v[4:7]
	v_mfma_f32_16x16x32_bf16 v[0:3], v[164:167], v[196:199], v[0:3]
	s_setprio 0
	s_barrier
	s_add_u32 s16, s16, 0x100
	s_addc_u32 s17, s17, 0
	s_cmp_ge_u32 s25, s12
	s_mov_b64 s[0:1], s[8:9]
	s_mov_b32 s24, s25
	s_cbranch_scc0 .LBB0_282
	s_and_b64 vcc, exec, s[80:81]
	s_cbranch_vccz .LBB0_285

; #define PG8_BAR __builtin_amdgcn_s_barrier()
; __device__ __forceinline__ void gemm_phase(LAS unsigned char* lds, const Call& C, const int tid, const Args& args) {
;     ...
;         if (wr == 1) PG8_BAR;
.LBB0_313:
	s_cmp_eq_u32 s101, 0
	s_cbranch_scc1 .Lbf1_nb2
	s_barrier

; #define PG8_BAR __builtin_amdgcn_s_barrier()
; __device__ __forceinline__ void gemm_phase(LAS unsigned char* lds, const Call& C, const int tid, const Args& args) {
;     ...
;         cur.pm = nxt.pm; cur.pn = nxt.pn; cur.kp0 = nxt.kp0; cur.np = nxt.np; cur.slice = nxt.slice; cA = nA; cB = nB; ++ui;
;         if (wr == 1) PG8_BAR;
.LBB0_496:
	v_readlane_b32 s0, v254, 57
	v_readlane_b32 s1, v254, 58
	s_mov_b32 s101, 0
	s_andn2_b64 vcc, exec, s[0:1]
	s_cbranch_vccnz .LBB0_265
	s_mov_b32 s101, 1
	s_branch .LBB0_265

; __device__ __forceinline__ void xcd_barrier(const XcdBarrier& b) {
;     asm volatile("s_waitcnt vmcnt(0)" ::: "memory");
;     __syncthreads();
;     if (tid_of(b.wave0) == 0) {
.LBB0_773:
	s_mov_b32 s2, -1
	s_waitcnt vmcnt(0)
	s_waitcnt vmcnt(0) lgkmcnt(0)
	s_barrier
	s_cmp_lg_u32 s95, 0xffffffc0
	s_cbranch_scc1 .Le1_notw1
	buffer_inv sc1
.Le1_notw1:
	s_nop 0
	v_mbcnt_lo_u32_b32 v0, s2, 0
	v_mbcnt_hi_u32_b32 v0, s2, v0
	v_cmp_eq_u32_e32 vcc, s95, v0
	s_and_saveexec_b64 s[2:3], vcc
	s_cbranch_execnz .LBB0_774
	s_getpc_b64 s[98:99]

; __device__ __forceinline__ unsigned xb_add(unsigned* p, unsigned v) { return __hip_atomic_fetch_add(p, v, __ATOMIC_RELAXED, __HIP_MEMORY_SCOPE_AGENT); }
; __device__ __forceinline__ void xcd_barrier(const XcdBarrier& b) {
;     ...
;         __builtin_amdgcn_s_waitcnt(0);
;         unsigned nloc = b.st[0], nx = b.st[1];
;         if (nloc == 0u) { xcd_barrier_complete(bar, b.x, nloc, nx); b.st[0] = nloc; b.st[1] = nx; }
;         const unsigned target = b.st[2] + nx;
;         __builtin_amdgcn_fence(__ATOMIC_ACQUIRE, "agent");
;         const unsigned old = xb_add(&bar[XB_XSUB(b.x)], 1u);
;         const unsigned gen = old / nloc;
;         if (old + 1u == (gen + 1u) * nloc) {
;             __builtin_amdgcn_fence(__ATOMIC_RELEASE, "agent");
;             asm volatile("s_waitcnt vmcnt(0)" ::: "memory");
;             (void)xb_add(&bar[XB_TOP], 1u);
;         }
.LBB0_788:
	v_readlane_b32 s4, v253, 29
	s_nop 1
	v_mov_b32_e32 v2, s4
	v_readlane_b32 s4, v253, 24
	s_add_u32 s4, s8, s4
	s_addc_u32 s5, s9, 0
	v_mov_b32_e32 v3, s4
	v_add_co_u32_e32 v4, vcc, 0x1000, v3
	v_mov_b32_e32 v3, s5
	s_nop 0
	v_addc_co_u32_e32 v5, vcc, 0, v3, vcc
	ds_read_b32 v2, v2
	s_waitcnt vmcnt(0) lgkmcnt(0)
	flat_atomic_add v3, v[4:5], v226 offset:1024 sc0
	v_cvt_f32_u32_e32 v4, v0
	v_sub_u32_e32 v5, 0, v0
	v_rcp_iflag_f32_e32 v4, v4
	s_nop 0
	v_mul_f32_e32 v4, 0x4f7ffffe, v4
	v_cvt_u32_f32_e32 v4, v4
	v_mul_lo_u32 v5, v5, v4
	v_mul_hi_u32 v5, v4, v5
	v_add_u32_e32 v4, v4, v5
	s_waitcnt vmcnt(0) lgkmcnt(0)
	v_mul_hi_u32 v4, v3, v4
	v_mul_lo_u32 v5, v4, v0
	v_sub_u32_e32 v5, v3, v5
	v_cmp_ge_u32_e32 vcc, v5, v0
	v_add_u32_e32 v6, 1, v4
	v_add_u32_e32 v3, 1, v3
	v_cndmask_b32_e32 v4, v4, v6, vcc
	v_sub_u32_e32 v6, v5, v0
	v_cndmask_b32_e32 v5, v5, v6, vcc
	v_cmp_ge_u32_e32 vcc, v5, v0
	v_add_u32_e32 v5, 1, v4
	s_nop 0
	v_cndmask_b32_e32 v4, v4, v5, vcc
	v_mad_u64_u32 v[4:5], s[4:5], v0, v4, v[0:1]
	v_cmp_eq_u32_e32 vcc, v3, v4
	s_and_saveexec_b64 s[12:13], vcc
	s_cbranch_execz .LBB0_790
	v_mov_b32_e32 v0, s8
	v_add_co_u32_e32 v4, vcc, 0x3000, v0
	v_mov_b32_e32 v0, s9
	v_addc_co_u32_e32 v5, vcc, 0, v0, vcc
	flat_atomic_add v[4:5], v226 offset:1024

; __global__ void __launch_bounds__(NTHR, 2) dit_fwd(Args args) {
	.amdhsa_kernel _Z7dit_fwd4Args
		.amdhsa_group_segment_fixed_size 0
		.amdhsa_private_segment_fixed_size 0
		.amdhsa_kernarg_size 432
		.amdhsa_user_sgpr_count 2
		.amdhsa_user_sgpr_dispatch_ptr 0
		.amdhsa_user_sgpr_queue_ptr 0
		.amdhsa_user_sgpr_kernarg_segment_ptr 1
		.amdhsa_user_sgpr_dispatch_id 0
		.amdhsa_user_sgpr_kernarg_preload_length 0
		.amdhsa_user_sgpr_kernarg_preload_offset 0
		.amdhsa_user_sgpr_private_segment_size 0
		.amdhsa_uses_dynamic_stack 0
		.amdhsa_enable_private_segment 0
		.amdhsa_system_sgpr_workgroup_id_x 1
		.amdhsa_system_sgpr_workgroup_id_y 0
		.amdhsa_system_sgpr_workgroup_id_z 0
		.amdhsa_system_sgpr_workgroup_info 0
		.amdhsa_system_vgpr_workitem_id 0
		.amdhsa_next_free_vgpr 256
		.amdhsa_next_free_sgpr 102
		.amdhsa_accum_offset 256
		.amdhsa_reserve_vcc 1
		.amdhsa_float_round_mode_32 0
		.amdhsa_float_round_mode_16_64 0
		.amdhsa_float_denorm_mode_32 3
		.amdhsa_float_denorm_mode_16_64 3
		.amdhsa_dx10_clamp 1
		.amdhsa_ieee_mode 1
		.amdhsa_fp16_overflow 0
		.amdhsa_tg_split 0
		.amdhsa_exception_fp_ieee_invalid_op 0
		.amdhsa_exception_fp_denorm_src 0
		.amdhsa_exception_fp_ieee_div_zero 0
		.amdhsa_exception_fp_ieee_overflow 0
		.amdhsa_exception_fp_ieee_underflow 0
		.amdhsa_exception_fp_ieee_inexact 0
		.amdhsa_exception_int_div_zero 0
	.end_amdhsa_kernel

; __global__ void __launch_bounds__(NTHR, 2) dit_fwd(Args args) {
amdhsa.kernels:
  - .agpr_count:     0
    .args:
      - .offset:         0
        .size:           176
        .value_kind:     by_value
      - .offset:         176
        .size:           4
        .value_kind:     hidden_block_count_x
      - .offset:         180
        .size:           4
        .value_kind:     hidden_block_count_y
      - .offset:         184
        .size:           4
        .value_kind:     hidden_block_count_z
      - .offset:         188
        .size:           2
        .value_kind:     hidden_group_size_x
      - .offset:         190
        .size:           2
        .value_kind:     hidden_group_size_y
      - .offset:         192
        .size:           2
        .value_kind:     hidden_group_size_z
      - .offset:         194
        .size:           2
        .value_kind:     hidden_remainder_x
      - .offset:         196
        .size:           2
        .value_kind:     hidden_remainder_y
      - .offset:         198
        .size:           2
        .value_kind:     hidden_remainder_z
      - .offset:         216
        .size:           8
        .value_kind:     hidden_global_offset_x
      - .offset:         224
        .size:           8
        .value_kind:     hidden_global_offset_y
      - .offset:         232
        .size:           8
        .value_kind:     hidden_global_offset_z
      - .offset:         240
        .size:           2
        .value_kind:     hidden_grid_dims
      - .offset:         296
        .size:           4
        .value_kind:     hidden_dynamic_lds_size
    .group_segment_fixed_size: 0
    .kernarg_segment_align: 8
    .kernarg_segment_size: 432
    .language:       OpenCL C
    .language_version:
      - 2
      - 0
    .max_flat_workgroup_size: 512
    .name:           _Z7dit_fwd4Args
    .private_segment_fixed_size: 0
    .sgpr_count:     108
    .sgpr_spill_count: 630
    .symbol:         _Z7dit_fwd4Args.kd
    .uniform_work_group_size: 1
    .uses_dynamic_stack: false
    .vgpr_count:     256
    .vgpr_spill_count: 0
    .wavefront_size: 64
